# v044 plus SGPR-base + 32-bit-offset form for the 16 LDS-DMA loads of the FFN-up K-loop (16 VALU 64-bit address adds removed)
# baseline (speedup 1.0000x reference)
; #define PG8_STAGE(bufoff, gbase, voff) do { _Pragma("unroll") for (int _i = 0; _i < 2; ++_i) \
;         __builtin_amdgcn_global_load_lds((const unsigned*)((const char*)(gbase) + (voff)[_i]), (LAS unsigned*)(lds + (bufoff) + ldsw + _i * 8192), 16, 0, 0); } while (0)
; #define PG8_LDA(dst, b, h) do { _Pragma("unroll") for (int m = 0; m < 4; ++m) _Pragma("unroll") for (int k = 0; k < 2; ++k) dst[m][k] = *(const LAS bf16x8*)(lds + PG8_SA(b, h) + aoff + m * 2048 + k * 1024); } while (0)
; #define PG8_LDB(dst, b, h) do { _Pragma("unroll") for (int n = 0; n < 2; ++n) _Pragma("unroll") for (int k = 0; k < 2; ++k) dst[n][k] = *(const LAS bf16x8*)(lds + PG8_SB(b, h) + boff + n * 2048 + k * 1024); } while (0)
; #define PG8_MMA(ai, bj, At, Bt) do { __builtin_amdgcn_s_setprio(1); _Pragma("unroll") for (int m = 0; m < 4; ++m) _Pragma("unroll") for (int n = 0; n < 2; ++n) _Pragma("unroll") for (int k = 0; k < 2; ++k) \
;         acc[ai][bj][m][n] = __builtin_amdgcn_mfma_f32_16x16x32_bf16(Bt[n][k], At[m][k], acc[ai][bj][m][n], 0, 0, 0); __builtin_amdgcn_s_setprio(0); } while (0)
; #define PG8_WAIT_V(n) asm volatile("s_waitcnt vmcnt(" #n ")" ::: "memory")
; #define PG8_WAIT_L(n) asm volatile("s_waitcnt lgkmcnt(" #n ")" ::: "memory")
; #define PG8_BAR __builtin_amdgcn_s_barrier()
; #define PG8_SCHED __builtin_amdgcn_sched_barrier(0)
; template <class Epi, bool ALIGN_EPI, bool SP2, bool ROWHALF = false>
; DI void gemm_phase(LAS unsigned char* lds, const Gemm g, const StaticOrder& S, const Epi& E) {
;     ...
;             if constexpr (SP2) {
;             PG8_LDB(B0, 0, 0); PG8_LDB(B1, 0, 1); PG8_SCHED; PG8_LDA(At, 0, 0); PG8_STAGE(PG8_SA(1, 1), a1 + hA1, voffA);
;             PG8_WAIT_V(8); PG8_WAIT_L(0); PG8_BAR; PG8_MMA(0, 0, At, B0); PG8_MMA(0, 1, At, B1); PG8_BAR; PG8_SCHED;
;             if constexpr (!ROWHALF) { PG8_LDA(At, 0, 1); } PG8_STAGE(PG8_SB(0, 0), b2, voffB); PG8_STAGE(PG8_SB(0, 1), b2 + hstepB, voffB); PG8_STAGE(PG8_SA(0, 0), a2 + hA0, voffA);
;             PG8_WAIT_V(8); PG8_WAIT_L(0); PG8_BAR; if constexpr (!ROWHALF) { PG8_MMA(1, 0, At, B0); PG8_MMA(1, 1, At, B1); } PG8_BAR; PG8_SCHED;
.Lk240_body:
	v_add_u32_e32 v156, s54, v145
	v_add_u32_e32 v160, s55, v145
	ds_read_b128 v[140:143], v156
	ds_read_b128 v[148:151], v156 offset:1024
	ds_read_b128 v[152:155], v156 offset:2048
	ds_read_b128 v[156:159], v156 offset:3072
	ds_read_b128 v[164:167], v160
	ds_read_b128 v[168:171], v160 offset:1024
	ds_read_b128 v[172:175], v160 offset:2048
	ds_read_b128 v[176:179], v160 offset:3072
	s_add_i32 m0, s9, 0xc000
	ds_read_b128 v[180:183], v147
	ds_read_b128 v[184:187], v147 offset:1024
	ds_read_b128 v[216:219], v147 offset:2048
	ds_read_b128 v[220:223], v147 offset:3072
	ds_read_b128 v[224:227], v147 offset:4096
	ds_read_b128 v[228:231], v147 offset:5120
	ds_read_b128 v[232:235], v147 offset:6144
	ds_read_b128 v[236:239], v147 offset:7168
	global_load_lds_dwordx4 v136, s[74:75]
	s_add_i32 m0, s9, 0xe000
	s_nop 0
	global_load_lds_dwordx4 v138, s[74:75]
	s_waitcnt vmcnt(8)
	s_waitcnt lgkmcnt(0)
	s_setprio 1
	v_mfma_f32_16x16x32_bf16 v[126:129], v[140:143], v[180:183], v[126:129]
	v_mfma_f32_16x16x32_bf16 v[118:121], v[152:155], v[180:183], v[118:121]
	v_mfma_f32_16x16x32_bf16 v[110:113], v[140:143], v[216:219], v[110:113]
	v_mfma_f32_16x16x32_bf16 v[102:105], v[152:155], v[216:219], v[102:105]
	s_barrier
	v_mfma_f32_16x16x32_bf16 v[92:95], v[140:143], v[224:227], v[92:95]
	v_mfma_f32_16x16x32_bf16 v[84:87], v[152:155], v[224:227], v[84:87]
	v_mfma_f32_16x16x32_bf16 v[76:79], v[140:143], v[232:235], v[76:79]
	v_mfma_f32_16x16x32_bf16 v[68:71], v[152:155], v[232:235], v[68:71]
	v_mfma_f32_16x16x32_bf16 v[126:129], v[148:151], v[184:187], v[126:129]
	v_mfma_f32_16x16x32_bf16 v[118:121], v[156:159], v[184:187], v[118:121]
	v_mfma_f32_16x16x32_bf16 v[110:113], v[148:151], v[220:223], v[110:113]
	v_mfma_f32_16x16x32_bf16 v[102:105], v[156:159], v[220:223], v[102:105]
	v_mfma_f32_16x16x32_bf16 v[92:95], v[148:151], v[228:231], v[92:95]
	v_mfma_f32_16x16x32_bf16 v[84:87], v[156:159], v[228:231], v[84:87]
	v_mfma_f32_16x16x32_bf16 v[76:79], v[148:151], v[236:239], v[76:79]
	v_mfma_f32_16x16x32_bf16 v[68:71], v[156:159], v[236:239], v[68:71]
	s_setprio 0
	s_setprio 1
	v_mfma_f32_16x16x32_bf16 v[122:125], v[164:167], v[180:183], v[122:125]
	v_mfma_f32_16x16x32_bf16 v[114:117], v[172:175], v[180:183], v[114:117]
	v_mfma_f32_16x16x32_bf16 v[106:109], v[164:167], v[216:219], v[106:109]
	v_mfma_f32_16x16x32_bf16 v[98:101], v[172:175], v[216:219], v[98:101]
	v_mfma_f32_16x16x32_bf16 v[88:91], v[164:167], v[224:227], v[88:91]
	v_mfma_f32_16x16x32_bf16 v[80:83], v[172:175], v[224:227], v[80:83]
	v_mfma_f32_16x16x32_bf16 v[72:75], v[164:167], v[232:235], v[72:75]
	v_mfma_f32_16x16x32_bf16 v[64:67], v[172:175], v[232:235], v[64:67]
	v_mfma_f32_16x16x32_bf16 v[122:125], v[168:171], v[184:187], v[122:125]
	v_mfma_f32_16x16x32_bf16 v[114:117], v[176:179], v[184:187], v[114:117]
	v_mfma_f32_16x16x32_bf16 v[106:109], v[168:171], v[220:223], v[106:109]
	v_mfma_f32_16x16x32_bf16 v[98:101], v[176:179], v[220:223], v[98:101]
	v_mfma_f32_16x16x32_bf16 v[88:91], v[168:171], v[228:231], v[88:91]
	v_mfma_f32_16x16x32_bf16 v[80:83], v[176:179], v[228:231], v[80:83]
	v_mfma_f32_16x16x32_bf16 v[72:75], v[168:171], v[236:239], v[72:75]
	v_mfma_f32_16x16x32_bf16 v[64:67], v[176:179], v[236:239], v[64:67]
	s_setprio 0
	s_barrier
	s_add_i32 s36, s54, s8
	s_mov_b32 m0, s36
	ds_read_b128 v[180:183], v147 offset:16384
	ds_read_b128 v[184:187], v147 offset:17408
	ds_read_b128 v[216:219], v147 offset:18432
	ds_read_b128 v[220:223], v147 offset:19456
	ds_read_b128 v[224:227], v147 offset:20480
	ds_read_b128 v[228:231], v147 offset:21504
	ds_read_b128 v[232:235], v147 offset:22528
	ds_read_b128 v[236:239], v147 offset:23552
	global_load_lds_dwordx4 v96, s[76:77]
	s_add_i32 m0, s36, 0x2000
	s_add_u32 s36, s76, 0x80000
	s_addc_u32 s37, s77, 0
	s_add_i32 s54, s55, s8
	global_load_lds_dwordx4 v130, s[76:77]
	s_mov_b32 m0, s54
	s_nop 0
	global_load_lds_dwordx4 v96, s[36:37]
	s_add_i32 m0, s54, 0x2000
	s_nop 0
	global_load_lds_dwordx4 v130, s[36:37]
	s_mov_b32 m0, s9
	s_nop 0
	global_load_lds_dwordx4 v134, s[78:79]
	s_mov_b32 m0, s10
	s_nop 0
	global_load_lds_dwordx4 v132, s[78:79]
	s_waitcnt vmcnt(8)
	s_waitcnt lgkmcnt(0)
	s_setprio 1
	v_mfma_f32_16x16x32_bf16 v[60:63], v[140:143], v[180:183], v[60:63]
	v_mfma_f32_16x16x32_bf16 v[52:55], v[152:155], v[180:183], v[52:55]
	v_mfma_f32_16x16x32_bf16 v[44:47], v[140:143], v[216:219], v[44:47]
	v_mfma_f32_16x16x32_bf16 v[36:39], v[152:155], v[216:219], v[36:39]
	s_barrier
	v_mfma_f32_16x16x32_bf16 v[28:31], v[140:143], v[224:227], v[28:31]
	v_mfma_f32_16x16x32_bf16 v[20:23], v[152:155], v[224:227], v[20:23]
	v_mfma_f32_16x16x32_bf16 v[12:15], v[140:143], v[232:235], v[12:15]
	v_mfma_f32_16x16x32_bf16 v[4:7], v[152:155], v[232:235], v[4:7]
	v_mfma_f32_16x16x32_bf16 v[60:63], v[148:151], v[184:187], v[60:63]
	v_mfma_f32_16x16x32_bf16 v[52:55], v[156:159], v[184:187], v[52:55]
	v_mfma_f32_16x16x32_bf16 v[44:47], v[148:151], v[220:223], v[44:47]
	v_mfma_f32_16x16x32_bf16 v[36:39], v[156:159], v[220:223], v[36:39]
	v_mfma_f32_16x16x32_bf16 v[28:31], v[148:151], v[228:231], v[28:31]
	v_mfma_f32_16x16x32_bf16 v[20:23], v[156:159], v[228:231], v[20:23]
	v_mfma_f32_16x16x32_bf16 v[12:15], v[148:151], v[236:239], v[12:15]
	v_mfma_f32_16x16x32_bf16 v[4:7], v[156:159], v[236:239], v[4:7]
	s_setprio 0
	s_setprio 1
	v_mfma_f32_16x16x32_bf16 v[56:59], v[164:167], v[180:183], v[56:59]
	v_mfma_f32_16x16x32_bf16 v[48:51], v[172:175], v[180:183], v[48:51]
	v_mfma_f32_16x16x32_bf16 v[40:43], v[164:167], v[216:219], v[40:43]
	v_mfma_f32_16x16x32_bf16 v[32:35], v[172:175], v[216:219], v[32:35]
	v_mfma_f32_16x16x32_bf16 v[24:27], v[164:167], v[224:227], v[24:27]
	v_mfma_f32_16x16x32_bf16 v[16:19], v[172:175], v[224:227], v[16:19]
	v_mfma_f32_16x16x32_bf16 v[8:11], v[164:167], v[232:235], v[8:11]
	v_mfma_f32_16x16x32_bf16 v[0:3], v[172:175], v[232:235], v[0:3]
	v_mfma_f32_16x16x32_bf16 v[56:59], v[168:171], v[184:187], v[56:59]
	v_mfma_f32_16x16x32_bf16 v[48:51], v[176:179], v[184:187], v[48:51]
	v_mfma_f32_16x16x32_bf16 v[40:43], v[168:171], v[220:223], v[40:43]
	v_mfma_f32_16x16x32_bf16 v[32:35], v[176:179], v[220:223], v[32:35]
	v_mfma_f32_16x16x32_bf16 v[24:27], v[168:171], v[228:231], v[24:27]
	v_mfma_f32_16x16x32_bf16 v[16:19], v[176:179], v[228:231], v[16:19]
	v_mfma_f32_16x16x32_bf16 v[8:11], v[168:171], v[236:239], v[8:11]
	v_mfma_f32_16x16x32_bf16 v[0:3], v[176:179], v[236:239], v[0:3]
	s_setprio 0
	s_barrier
; #define PG8_STAGE(bufoff, gbase, voff) do { _Pragma("unroll") for (int _i = 0; _i < 2; ++_i) \
;         __builtin_amdgcn_global_load_lds((const unsigned*)((const char*)(gbase) + (voff)[_i]), (LAS unsigned*)(lds + (bufoff) + ldsw + _i * 8192), 16, 0, 0); } while (0)
; #define PG8_LDA(dst, b, h) do { _Pragma("unroll") for (int m = 0; m < 4; ++m) _Pragma("unroll") for (int k = 0; k < 2; ++k) dst[m][k] = *(const LAS bf16x8*)(lds + PG8_SA(b, h) + aoff + m * 2048 + k * 1024); } while (0)
; #define PG8_LDB(dst, b, h) do { _Pragma("unroll") for (int n = 0; n < 2; ++n) _Pragma("unroll") for (int k = 0; k < 2; ++k) dst[n][k] = *(const LAS bf16x8*)(lds + PG8_SB(b, h) + boff + n * 2048 + k * 1024); } while (0)
; #define PG8_MMA(ai, bj, At, Bt) do { __builtin_amdgcn_s_setprio(1); _Pragma("unroll") for (int m = 0; m < 4; ++m) _Pragma("unroll") for (int n = 0; n < 2; ++n) _Pragma("unroll") for (int k = 0; k < 2; ++k) \
;         acc[ai][bj][m][n] = __builtin_amdgcn_mfma_f32_16x16x32_bf16(Bt[n][k], At[m][k], acc[ai][bj][m][n], 0, 0, 0); __builtin_amdgcn_s_setprio(0); } while (0)
; #define PG8_WAIT_V(n) asm volatile("s_waitcnt vmcnt(" #n ")" ::: "memory")
; #define PG8_WAIT_L(n) asm volatile("s_waitcnt lgkmcnt(" #n ")" ::: "memory")
; #define PG8_BAR __builtin_amdgcn_s_barrier()
; #define PG8_SCHED __builtin_amdgcn_sched_barrier(0)
; template <class Epi, bool ALIGN_EPI, bool SP2, bool ROWHALF = false>
; DI void gemm_phase(LAS unsigned char* lds, const Gemm g, const StaticOrder& S, const Epi& E) {
;     ...
;             PG8_LDB(B0, 1, 0); PG8_LDB(B1, 1, 1); PG8_SCHED; PG8_LDA(At, 1, 0); PG8_STAGE(PG8_SA(0, 1), a2 + hA1, voffA);
;             PG8_WAIT_V(8); PG8_WAIT_L(0); PG8_BAR; PG8_MMA(0, 0, At, B0); PG8_MMA(0, 1, At, B1); PG8_BAR; PG8_SCHED;
	s_add_i32 s54, 0, 0x18000
	s_add_i32 s55, 0, 0x1c000
	v_add_u32_e32 v156, s54, v145
	v_add_u32_e32 v176, s55, v145
	ds_read_b128 v[140:143], v156
	ds_read_b128 v[148:151], v156 offset:1024
	ds_read_b128 v[152:155], v156 offset:2048
	ds_read_b128 v[156:159], v156 offset:3072
	ds_read_b128 v[164:167], v176
	ds_read_b128 v[168:171], v176 offset:1024
	ds_read_b128 v[172:175], v176 offset:2048
	ds_read_b128 v[176:179], v176 offset:3072
	s_add_u32 s36, s78, 0x80000
	s_addc_u32 s37, s79, 0
	s_mov_b32 m0, s11
	ds_read_b128 v[180:183], v147 offset:32768
	ds_read_b128 v[184:187], v147 offset:33792
	ds_read_b128 v[216:219], v147 offset:34816
	ds_read_b128 v[220:223], v147 offset:35840
	ds_read_b128 v[224:227], v147 offset:36864
	ds_read_b128 v[228:231], v147 offset:37888
	ds_read_b128 v[232:235], v147 offset:38912
	ds_read_b128 v[236:239], v147 offset:39936
	global_load_lds_dwordx4 v134, s[36:37]
	s_mov_b32 m0, s12
	s_nop 0
	global_load_lds_dwordx4 v132, s[36:37]
	s_waitcnt vmcnt(8)
	s_waitcnt lgkmcnt(0)
	s_setprio 1
	v_mfma_f32_16x16x32_bf16 v[126:129], v[140:143], v[180:183], v[126:129]
	v_mfma_f32_16x16x32_bf16 v[118:121], v[152:155], v[180:183], v[118:121]
	v_mfma_f32_16x16x32_bf16 v[110:113], v[140:143], v[216:219], v[110:113]
	v_mfma_f32_16x16x32_bf16 v[102:105], v[152:155], v[216:219], v[102:105]
	s_barrier
	v_mfma_f32_16x16x32_bf16 v[92:95], v[140:143], v[224:227], v[92:95]
	v_mfma_f32_16x16x32_bf16 v[84:87], v[152:155], v[224:227], v[84:87]
	v_mfma_f32_16x16x32_bf16 v[76:79], v[140:143], v[232:235], v[76:79]
	v_mfma_f32_16x16x32_bf16 v[68:71], v[152:155], v[232:235], v[68:71]
	v_mfma_f32_16x16x32_bf16 v[126:129], v[148:151], v[184:187], v[126:129]
	v_mfma_f32_16x16x32_bf16 v[118:121], v[156:159], v[184:187], v[118:121]
	v_mfma_f32_16x16x32_bf16 v[110:113], v[148:151], v[220:223], v[110:113]
	v_mfma_f32_16x16x32_bf16 v[102:105], v[156:159], v[220:223], v[102:105]
	v_mfma_f32_16x16x32_bf16 v[92:95], v[148:151], v[228:231], v[92:95]
	v_mfma_f32_16x16x32_bf16 v[84:87], v[156:159], v[228:231], v[84:87]
	v_mfma_f32_16x16x32_bf16 v[76:79], v[148:151], v[236:239], v[76:79]
	v_mfma_f32_16x16x32_bf16 v[68:71], v[156:159], v[236:239], v[68:71]
	s_setprio 0
	s_setprio 1
	v_mfma_f32_16x16x32_bf16 v[122:125], v[164:167], v[180:183], v[122:125]
	v_mfma_f32_16x16x32_bf16 v[114:117], v[172:175], v[180:183], v[114:117]
	v_mfma_f32_16x16x32_bf16 v[106:109], v[164:167], v[216:219], v[106:109]
	v_mfma_f32_16x16x32_bf16 v[98:101], v[172:175], v[216:219], v[98:101]
	v_mfma_f32_16x16x32_bf16 v[88:91], v[164:167], v[224:227], v[88:91]
	v_mfma_f32_16x16x32_bf16 v[80:83], v[172:175], v[224:227], v[80:83]
	v_mfma_f32_16x16x32_bf16 v[72:75], v[164:167], v[232:235], v[72:75]
	v_mfma_f32_16x16x32_bf16 v[64:67], v[172:175], v[232:235], v[64:67]
	v_mfma_f32_16x16x32_bf16 v[122:125], v[168:171], v[184:187], v[122:125]
	v_mfma_f32_16x16x32_bf16 v[114:117], v[176:179], v[184:187], v[114:117]
	v_mfma_f32_16x16x32_bf16 v[106:109], v[168:171], v[220:223], v[106:109]
	v_mfma_f32_16x16x32_bf16 v[98:101], v[176:179], v[220:223], v[98:101]
	v_mfma_f32_16x16x32_bf16 v[88:91], v[168:171], v[228:231], v[88:91]
	v_mfma_f32_16x16x32_bf16 v[80:83], v[176:179], v[228:231], v[80:83]
	v_mfma_f32_16x16x32_bf16 v[72:75], v[168:171], v[236:239], v[72:75]
	v_mfma_f32_16x16x32_bf16 v[64:67], v[176:179], v[236:239], v[64:67]
	s_setprio 0
	s_barrier
; #define PG8_STAGE(bufoff, gbase, voff) do { _Pragma("unroll") for (int _i = 0; _i < 2; ++_i) \
;         __builtin_amdgcn_global_load_lds((const unsigned*)((const char*)(gbase) + (voff)[_i]), (LAS unsigned*)(lds + (bufoff) + ldsw + _i * 8192), 16, 0, 0); } while (0)
; #define PG8_LDA(dst, b, h) do { _Pragma("unroll") for (int m = 0; m < 4; ++m) _Pragma("unroll") for (int k = 0; k < 2; ++k) dst[m][k] = *(const LAS bf16x8*)(lds + PG8_SA(b, h) + aoff + m * 2048 + k * 1024); } while (0)
; #define PG8_MMA(ai, bj, At, Bt) do { __builtin_amdgcn_s_setprio(1); _Pragma("unroll") for (int m = 0; m < 4; ++m) _Pragma("unroll") for (int n = 0; n < 2; ++n) _Pragma("unroll") for (int k = 0; k < 2; ++k) \
;         acc[ai][bj][m][n] = __builtin_amdgcn_mfma_f32_16x16x32_bf16(Bt[n][k], At[m][k], acc[ai][bj][m][n], 0, 0, 0); __builtin_amdgcn_s_setprio(0); } while (0)
; #define PG8_WAIT_V(n) asm volatile("s_waitcnt vmcnt(" #n ")" ::: "memory")
; #define PG8_WAIT_L(n) asm volatile("s_waitcnt lgkmcnt(" #n ")" ::: "memory")
; #define PG8_BAR __builtin_amdgcn_s_barrier()
; #define PG8_SCHED __builtin_amdgcn_sched_barrier(0)
; template <class Epi, bool ALIGN_EPI, bool SP2, bool ROWHALF = false>
; DI void gemm_phase(LAS unsigned char* lds, const Gemm g, const StaticOrder& S, const Epi& E) {
;     ...
;             if constexpr (!ROWHALF) { PG8_LDA(At, 1, 1); } PG8_STAGE(PG8_SB(1, 0), b3, voffB); PG8_STAGE(PG8_SB(1, 1), b3 + hstepB, voffB); PG8_STAGE(PG8_SA(1, 0), a3 + hA0, voffA);
;             PG8_WAIT_V(8); PG8_WAIT_L(0); PG8_BAR; if constexpr (!ROWHALF) { PG8_MMA(1, 0, At, B0); PG8_MMA(1, 1, At, B1); } PG8_BAR; PG8_SCHED;
	s_add_i32 s36, s54, s8
	s_add_u32 s100, s76, 0x80
	s_addc_u32 s101, s77, 0
	s_mov_b32 m0, s36
	ds_read_b128 v[180:183], v147 offset:49152
	ds_read_b128 v[184:187], v147 offset:50176
	ds_read_b128 v[216:219], v147 offset:51200
	ds_read_b128 v[220:223], v147 offset:52224
	ds_read_b128 v[224:227], v147 offset:53248
	ds_read_b128 v[228:231], v147 offset:54272
	ds_read_b128 v[232:235], v147 offset:55296
	ds_read_b128 v[236:239], v147 offset:56320
	global_load_lds_dwordx4 v96, s[100:101]
	s_add_i32 m0, s36, 0x2000
	s_add_u32 s36, s76, 0x80080
	s_addc_u32 s37, s77, 0
	s_add_i32 s54, s55, s8
	global_load_lds_dwordx4 v130, s[100:101]
	s_add_u32 s100, s78, 0x80
	s_addc_u32 s101, s79, 0
	s_mov_b32 m0, s54
	s_nop 0
	global_load_lds_dwordx4 v96, s[36:37]
	s_add_i32 m0, s54, 0x2000
	s_nop 0
	global_load_lds_dwordx4 v130, s[36:37]
	s_mov_b32 m0, s31
	s_nop 0
	global_load_lds_dwordx4 v134, s[100:101]
	s_mov_b32 m0, s46
	s_nop 0
	global_load_lds_dwordx4 v132, s[100:101]
	s_waitcnt vmcnt(8)
	s_waitcnt lgkmcnt(0)
	s_setprio 1
	v_mfma_f32_16x16x32_bf16 v[60:63], v[140:143], v[180:183], v[60:63]
	v_mfma_f32_16x16x32_bf16 v[52:55], v[152:155], v[180:183], v[52:55]
	v_mfma_f32_16x16x32_bf16 v[44:47], v[140:143], v[216:219], v[44:47]
	v_mfma_f32_16x16x32_bf16 v[36:39], v[152:155], v[216:219], v[36:39]
	s_barrier
	v_mfma_f32_16x16x32_bf16 v[28:31], v[140:143], v[224:227], v[28:31]
	v_mfma_f32_16x16x32_bf16 v[20:23], v[152:155], v[224:227], v[20:23]
	v_mfma_f32_16x16x32_bf16 v[12:15], v[140:143], v[232:235], v[12:15]
	v_mfma_f32_16x16x32_bf16 v[4:7], v[152:155], v[232:235], v[4:7]
	v_mfma_f32_16x16x32_bf16 v[60:63], v[148:151], v[184:187], v[60:63]
	v_mfma_f32_16x16x32_bf16 v[52:55], v[156:159], v[184:187], v[52:55]
	v_mfma_f32_16x16x32_bf16 v[44:47], v[148:151], v[220:223], v[44:47]
	v_mfma_f32_16x16x32_bf16 v[36:39], v[156:159], v[220:223], v[36:39]
	v_mfma_f32_16x16x32_bf16 v[28:31], v[148:151], v[228:231], v[28:31]
	v_mfma_f32_16x16x32_bf16 v[20:23], v[156:159], v[228:231], v[20:23]
	v_mfma_f32_16x16x32_bf16 v[12:15], v[148:151], v[236:239], v[12:15]
	v_mfma_f32_16x16x32_bf16 v[4:7], v[156:159], v[236:239], v[4:7]
	s_setprio 0
	s_setprio 1
	v_mfma_f32_16x16x32_bf16 v[56:59], v[164:167], v[180:183], v[56:59]
	s_add_i32 s53, s53, 2
	v_mfma_f32_16x16x32_bf16 v[48:51], v[172:175], v[180:183], v[48:51]
	s_add_u32 s74, s74, 0x100
	s_addc_u32 s75, s75, 0
	v_mfma_f32_16x16x32_bf16 v[40:43], v[164:167], v[216:219], v[40:43]
	s_add_u32 s47, s47, 0x100
	s_addc_u32 s51, s51, 0
	v_mfma_f32_16x16x32_bf16 v[32:35], v[172:175], v[216:219], v[32:35]
	s_add_u32 s36, s74, 0xfff80080
	s_addc_u32 s37, s75, -1
	v_mfma_f32_16x16x32_bf16 v[24:27], v[164:167], v[224:227], v[24:27]
	s_add_i32 s54, 0, 0x10000
	v_mfma_f32_16x16x32_bf16 v[16:19], v[172:175], v[224:227], v[16:19]
	s_cmp_eq_u32 s53, 28
	s_cselect_b32 s79, s20, s37
	v_mfma_f32_16x16x32_bf16 v[8:11], v[164:167], v[232:235], v[8:11]
	s_cselect_b32 s78, s21, s36
	s_cselect_b32 s77, s29, s51
	v_mfma_f32_16x16x32_bf16 v[0:3], v[172:175], v[232:235], v[0:3]
	s_cselect_b32 s76, s43, s47
	s_add_i32 s55, 0, 0x14000
	v_mfma_f32_16x16x32_bf16 v[56:59], v[168:171], v[184:187], v[56:59]
	v_mfma_f32_16x16x32_bf16 v[48:51], v[176:179], v[184:187], v[48:51]
	v_mfma_f32_16x16x32_bf16 v[40:43], v[168:171], v[220:223], v[40:43]
	v_mfma_f32_16x16x32_bf16 v[32:35], v[176:179], v[220:223], v[32:35]
	v_mfma_f32_16x16x32_bf16 v[24:27], v[168:171], v[228:231], v[24:27]
	v_mfma_f32_16x16x32_bf16 v[16:19], v[176:179], v[228:231], v[16:19]
	v_mfma_f32_16x16x32_bf16 v[8:11], v[168:171], v[236:239], v[8:11]
	v_mfma_f32_16x16x32_bf16 v[0:3], v[176:179], v[236:239], v[0:3]
	s_setprio 0
	s_cmp_gt_u32 s53, 29
	s_barrier
	s_cbranch_scc0 .Lk240_body
	s_and_b64 vcc, exec, s[24:25]
	s_cbranch_vccz .LBB0_243
	s_barrier
